# first K-loop iteration peeled with C=0 on each accumulator's first MFMA; per-unit accumulator zeroing removed
# speedup vs baseline: 1.0076x; 1.0076x over previous
.LBB0_231:
	s_ashr_i32 s77, s76, 31
	s_lshl_b64 s[66:67], s[76:77], 19
	s_add_u32 s80, s12, s66
	s_addc_u32 s81, s13, s67
	s_and_b64 s[66:67], s[78:79], exec
	s_cselect_b32 s66, s81, s85
	s_cselect_b32 s67, s80, s84
	s_ashr_i32 s75, s74, 31
	s_lshl_b64 s[68:69], s[74:75], 19
	s_add_u32 s82, s5, s68
	s_addc_u32 s83, s20, s69
	s_and_b64 s[68:69], s[78:79], exec
	s_cselect_b32 s68, s83, s87
	s_cselect_b32 s69, s82, s86
	s_add_u32 s84, s84, 0x40080
	s_addc_u32 s85, s85, 0
	s_add_u32 s75, s86, 0x100
	s_addc_u32 s77, s87, 0
	s_mov_b32 s90, -2
	s_waitcnt vmcnt(0)
	s_add_u32 s0, s84, 0xfffc0080
	s_addc_u32 s86, s85, -1
	s_add_i32 s96, 0, 0x10000
	s_cmp_eq_u32 s90, 12
	s_cselect_b32 s89, s66, s86
	s_cselect_b32 s88, s67, s0
	s_cselect_b32 s87, s68, s77
	s_cselect_b32 s86, s69, s75
	s_add_i32 s0, 0, 0x14000
	v_add_u32_e32 v160, s96, v145
	v_add_u32_e32 v176, s0, v145
	ds_read_b128 v[140:143], v160
	ds_read_b128 v[152:155], v160 offset:1024
	ds_read_b128 v[156:159], v160 offset:2048
	ds_read_b128 v[160:163], v160 offset:3072
	ds_read_b128 v[164:167], v176
	ds_read_b128 v[168:171], v176 offset:1024
	ds_read_b128 v[172:175], v176 offset:2048
	ds_read_b128 v[176:179], v176 offset:3072
	v_lshl_add_u64 v[180:181], s[84:85], 0, v[136:137]
	s_add_i32 m0, s22, 0xc000
	ds_read_b128 v[188:191], v151
	ds_read_b128 v[220:223], v151 offset:1024
	ds_read_b128 v[224:227], v151 offset:2048
	ds_read_b128 v[228:231], v151 offset:3072
	ds_read_b128 v[232:235], v151 offset:4096
	ds_read_b128 v[236:239], v151 offset:5120
	ds_read_b128 v[240:243], v151 offset:6144
	ds_read_b128 v[244:247], v151 offset:7168
	global_load_lds_dwordx4 v[180:181], off
	v_lshl_add_u64 v[180:181], s[84:85], 0, v[138:139]
	s_add_i32 m0, s22, 0xe000
	s_nop 0
	global_load_lds_dwordx4 v[180:181], off
	s_waitcnt vmcnt(8)
	s_waitcnt lgkmcnt(0)
	s_barrier
	s_setprio 1
	s_waitcnt lgkmcnt(0)
	v_mfma_f32_16x16x32_bf16 v[128:131], v[140:143], v[188:191], 0
	v_mfma_f32_16x16x32_bf16 v[124:127], v[156:159], v[188:191], 0
	v_mfma_f32_16x16x32_bf16 v[112:115], v[140:143], v[224:227], 0
	v_mfma_f32_16x16x32_bf16 v[108:111], v[156:159], v[224:227], 0
	v_mfma_f32_16x16x32_bf16 v[92:95], v[140:143], v[232:235], 0
	v_mfma_f32_16x16x32_bf16 v[88:91], v[156:159], v[232:235], 0
	v_mfma_f32_16x16x32_bf16 v[76:79], v[140:143], v[240:243], 0
	v_mfma_f32_16x16x32_bf16 v[72:75], v[156:159], v[240:243], 0
	v_mfma_f32_16x16x32_bf16 v[128:131], v[152:155], v[220:223], v[128:131]
	v_mfma_f32_16x16x32_bf16 v[124:127], v[160:163], v[220:223], v[124:127]
	v_mfma_f32_16x16x32_bf16 v[112:115], v[152:155], v[228:231], v[112:115]
	v_mfma_f32_16x16x32_bf16 v[108:111], v[160:163], v[228:231], v[108:111]
	v_mfma_f32_16x16x32_bf16 v[92:95], v[152:155], v[236:239], v[92:95]
	v_mfma_f32_16x16x32_bf16 v[88:91], v[160:163], v[236:239], v[88:91]
	v_mfma_f32_16x16x32_bf16 v[76:79], v[152:155], v[244:247], v[76:79]
	v_mfma_f32_16x16x32_bf16 v[72:75], v[160:163], v[244:247], v[72:75]
	s_setprio 0
	s_setprio 1
	v_mfma_f32_16x16x32_bf16 v[120:123], v[164:167], v[188:191], 0
	v_mfma_f32_16x16x32_bf16 v[116:119], v[172:175], v[188:191], 0
	v_mfma_f32_16x16x32_bf16 v[104:107], v[164:167], v[224:227], 0
	v_mfma_f32_16x16x32_bf16 v[100:103], v[172:175], v[224:227], 0
	v_mfma_f32_16x16x32_bf16 v[84:87], v[164:167], v[232:235], 0
	v_mfma_f32_16x16x32_bf16 v[80:83], v[172:175], v[232:235], 0
	v_mfma_f32_16x16x32_bf16 v[68:71], v[164:167], v[240:243], 0
	v_mfma_f32_16x16x32_bf16 v[64:67], v[172:175], v[240:243], 0
	v_mfma_f32_16x16x32_bf16 v[120:123], v[168:171], v[220:223], v[120:123]
	v_mfma_f32_16x16x32_bf16 v[116:119], v[176:179], v[220:223], v[116:119]
	v_mfma_f32_16x16x32_bf16 v[104:107], v[168:171], v[228:231], v[104:107]
	v_mfma_f32_16x16x32_bf16 v[100:103], v[176:179], v[228:231], v[100:103]
	v_mfma_f32_16x16x32_bf16 v[84:87], v[168:171], v[236:239], v[84:87]
	v_mfma_f32_16x16x32_bf16 v[80:83], v[176:179], v[236:239], v[80:83]
	v_mfma_f32_16x16x32_bf16 v[68:71], v[168:171], v[244:247], v[68:71]
	v_mfma_f32_16x16x32_bf16 v[64:67], v[176:179], v[244:247], v[64:67]
	s_setprio 0
	s_barrier
	s_add_i32 s96, s96, s1
	v_lshl_add_u64 v[180:181], s[86:87], 0, v[98:99]
	s_mov_b32 m0, s96
	ds_read_b128 v[188:191], v151 offset:16384
	ds_read_b128 v[220:223], v151 offset:17408
	ds_read_b128 v[224:227], v151 offset:18432
	ds_read_b128 v[228:231], v151 offset:19456
	ds_read_b128 v[232:235], v151 offset:20480
	ds_read_b128 v[236:239], v151 offset:21504
	ds_read_b128 v[240:243], v151 offset:22528
	ds_read_b128 v[244:247], v151 offset:23552
	global_load_lds_dwordx4 v[180:181], off
	s_add_i32 m0, s96, 0x2000
	s_add_u32 s96, s86, 0x40000
	v_lshl_add_u64 v[192:193], s[86:87], 0, v[134:135]
	s_addc_u32 s97, s87, 0
	s_add_i32 s0, s0, s1
	global_load_lds_dwordx4 v[192:193], off
	v_lshl_add_u64 v[248:249], s[96:97], 0, v[98:99]
	s_mov_b32 m0, s0
	v_lshl_add_u64 v[250:251], s[88:89], 0, v[132:133]
	global_load_lds_dwordx4 v[248:249], off
	v_lshl_add_u64 v[248:249], s[96:97], 0, v[134:135]
	s_add_i32 m0, s0, 0x2000
	s_nop 0
	global_load_lds_dwordx4 v[248:249], off
	v_lshl_add_u64 v[248:249], s[88:89], 0, v[96:97]
	s_mov_b32 m0, s22
	s_nop 0
	global_load_lds_dwordx4 v[248:249], off
	s_mov_b32 m0, s23
	s_nop 0
	global_load_lds_dwordx4 v[250:251], off
	s_waitcnt vmcnt(8)
	s_waitcnt lgkmcnt(0)
	s_barrier
	s_setprio 1
	s_waitcnt lgkmcnt(0)
	v_mfma_f32_16x16x32_bf16 v[60:63], v[140:143], v[188:191], 0
	v_mfma_f32_16x16x32_bf16 v[56:59], v[156:159], v[188:191], 0
	v_mfma_f32_16x16x32_bf16 v[44:47], v[140:143], v[224:227], 0
	v_mfma_f32_16x16x32_bf16 v[40:43], v[156:159], v[224:227], 0
	v_mfma_f32_16x16x32_bf16 v[28:31], v[140:143], v[232:235], 0
	v_mfma_f32_16x16x32_bf16 v[24:27], v[156:159], v[232:235], 0
	v_mfma_f32_16x16x32_bf16 v[12:15], v[140:143], v[240:243], 0
	v_mfma_f32_16x16x32_bf16 v[8:11], v[156:159], v[240:243], 0
	v_mfma_f32_16x16x32_bf16 v[60:63], v[152:155], v[220:223], v[60:63]
	v_mfma_f32_16x16x32_bf16 v[56:59], v[160:163], v[220:223], v[56:59]
	v_mfma_f32_16x16x32_bf16 v[44:47], v[152:155], v[228:231], v[44:47]
	v_mfma_f32_16x16x32_bf16 v[40:43], v[160:163], v[228:231], v[40:43]
	v_mfma_f32_16x16x32_bf16 v[28:31], v[152:155], v[236:239], v[28:31]
	v_mfma_f32_16x16x32_bf16 v[24:27], v[160:163], v[236:239], v[24:27]
	v_mfma_f32_16x16x32_bf16 v[12:15], v[152:155], v[244:247], v[12:15]
	v_mfma_f32_16x16x32_bf16 v[8:11], v[160:163], v[244:247], v[8:11]
	s_setprio 0
	s_setprio 1
	v_mfma_f32_16x16x32_bf16 v[52:55], v[164:167], v[188:191], 0
	v_mfma_f32_16x16x32_bf16 v[48:51], v[172:175], v[188:191], 0
	v_mfma_f32_16x16x32_bf16 v[36:39], v[164:167], v[224:227], 0
	v_mfma_f32_16x16x32_bf16 v[32:35], v[172:175], v[224:227], 0
	v_mfma_f32_16x16x32_bf16 v[20:23], v[164:167], v[232:235], 0
	v_mfma_f32_16x16x32_bf16 v[16:19], v[172:175], v[232:235], 0
	v_mfma_f32_16x16x32_bf16 v[4:7], v[164:167], v[240:243], 0
	v_mfma_f32_16x16x32_bf16 v[0:3], v[172:175], v[240:243], 0
	v_mfma_f32_16x16x32_bf16 v[52:55], v[168:171], v[220:223], v[52:55]
	v_mfma_f32_16x16x32_bf16 v[48:51], v[176:179], v[220:223], v[48:51]
	v_mfma_f32_16x16x32_bf16 v[36:39], v[168:171], v[228:231], v[36:39]
	v_mfma_f32_16x16x32_bf16 v[32:35], v[176:179], v[228:231], v[32:35]
	v_mfma_f32_16x16x32_bf16 v[20:23], v[168:171], v[236:239], v[20:23]
	v_mfma_f32_16x16x32_bf16 v[16:19], v[176:179], v[236:239], v[16:19]
	v_mfma_f32_16x16x32_bf16 v[4:7], v[168:171], v[244:247], v[4:7]
	v_mfma_f32_16x16x32_bf16 v[0:3], v[176:179], v[244:247], v[0:3]
	s_setprio 0
	s_barrier
	s_add_i32 s0, 0, 0x18000
	s_add_i32 s96, 0, 0x1c000
	v_add_u32_e32 v160, s0, v145
	v_add_u32_e32 v176, s96, v145
	ds_read_b128 v[140:143], v160
	ds_read_b128 v[152:155], v160 offset:1024
	ds_read_b128 v[156:159], v160 offset:2048
	ds_read_b128 v[160:163], v160 offset:3072
	ds_read_b128 v[164:167], v176
	ds_read_b128 v[168:171], v176 offset:1024
	ds_read_b128 v[172:175], v176 offset:2048
	ds_read_b128 v[176:179], v176 offset:3072
	s_add_u32 s88, s88, 0x40000
	s_addc_u32 s89, s89, 0
	s_mov_b32 m0, s26
	v_lshl_add_u64 v[252:253], s[88:89], 0, v[96:97]
	ds_read_b128 v[188:191], v151 offset:32768
	ds_read_b128 v[220:223], v151 offset:33792
	ds_read_b128 v[224:227], v151 offset:34816
	ds_read_b128 v[228:231], v151 offset:35840
	ds_read_b128 v[232:235], v151 offset:36864
	ds_read_b128 v[236:239], v151 offset:37888
	ds_read_b128 v[240:243], v151 offset:38912
	ds_read_b128 v[244:247], v151 offset:39936
	global_load_lds_dwordx4 v[252:253], off
	v_lshl_add_u64 v[252:253], s[88:89], 0, v[132:133]
	s_mov_b32 m0, s27
	s_nop 0
	global_load_lds_dwordx4 v[252:253], off
	s_waitcnt vmcnt(8)
	s_waitcnt lgkmcnt(0)
	s_barrier
	s_setprio 1
	s_waitcnt lgkmcnt(0)
	v_mfma_f32_16x16x32_bf16 v[128:131], v[140:143], v[188:191], v[128:131]
	v_mfma_f32_16x16x32_bf16 v[124:127], v[156:159], v[188:191], v[124:127]
	v_mfma_f32_16x16x32_bf16 v[112:115], v[140:143], v[224:227], v[112:115]
	v_mfma_f32_16x16x32_bf16 v[108:111], v[156:159], v[224:227], v[108:111]
	v_mfma_f32_16x16x32_bf16 v[92:95], v[140:143], v[232:235], v[92:95]
	v_mfma_f32_16x16x32_bf16 v[88:91], v[156:159], v[232:235], v[88:91]
	v_mfma_f32_16x16x32_bf16 v[76:79], v[140:143], v[240:243], v[76:79]
	v_mfma_f32_16x16x32_bf16 v[72:75], v[156:159], v[240:243], v[72:75]
	v_mfma_f32_16x16x32_bf16 v[128:131], v[152:155], v[220:223], v[128:131]
	v_mfma_f32_16x16x32_bf16 v[124:127], v[160:163], v[220:223], v[124:127]
	v_mfma_f32_16x16x32_bf16 v[112:115], v[152:155], v[228:231], v[112:115]
	v_mfma_f32_16x16x32_bf16 v[108:111], v[160:163], v[228:231], v[108:111]
	v_mfma_f32_16x16x32_bf16 v[92:95], v[152:155], v[236:239], v[92:95]
	v_mfma_f32_16x16x32_bf16 v[88:91], v[160:163], v[236:239], v[88:91]
	v_mfma_f32_16x16x32_bf16 v[76:79], v[152:155], v[244:247], v[76:79]
	v_mfma_f32_16x16x32_bf16 v[72:75], v[160:163], v[244:247], v[72:75]
	s_setprio 0
	s_setprio 1
	v_mfma_f32_16x16x32_bf16 v[120:123], v[164:167], v[188:191], v[120:123]
	v_mfma_f32_16x16x32_bf16 v[116:119], v[172:175], v[188:191], v[116:119]
	v_mfma_f32_16x16x32_bf16 v[104:107], v[164:167], v[224:227], v[104:107]
	v_mfma_f32_16x16x32_bf16 v[100:103], v[172:175], v[224:227], v[100:103]
	v_mfma_f32_16x16x32_bf16 v[84:87], v[164:167], v[232:235], v[84:87]
	v_mfma_f32_16x16x32_bf16 v[80:83], v[172:175], v[232:235], v[80:83]
	v_mfma_f32_16x16x32_bf16 v[68:71], v[164:167], v[240:243], v[68:71]
	v_mfma_f32_16x16x32_bf16 v[64:67], v[172:175], v[240:243], v[64:67]
	v_mfma_f32_16x16x32_bf16 v[120:123], v[168:171], v[220:223], v[120:123]
	v_mfma_f32_16x16x32_bf16 v[116:119], v[176:179], v[220:223], v[116:119]
	v_mfma_f32_16x16x32_bf16 v[104:107], v[168:171], v[228:231], v[104:107]
	v_mfma_f32_16x16x32_bf16 v[100:103], v[176:179], v[228:231], v[100:103]
	v_mfma_f32_16x16x32_bf16 v[84:87], v[168:171], v[236:239], v[84:87]
	v_mfma_f32_16x16x32_bf16 v[80:83], v[176:179], v[236:239], v[80:83]
	v_mfma_f32_16x16x32_bf16 v[68:71], v[168:171], v[244:247], v[68:71]
	v_mfma_f32_16x16x32_bf16 v[64:67], v[176:179], v[244:247], v[64:67]
	s_setprio 0
	s_barrier
	s_add_i32 s0, s0, s1
	v_lshl_add_u64 v[180:181], v[180:181], 0, s[58:59]
	s_mov_b32 m0, s0
	ds_read_b128 v[188:191], v151 offset:49152
	ds_read_b128 v[220:223], v151 offset:50176
	ds_read_b128 v[224:227], v151 offset:51200
	ds_read_b128 v[228:231], v151 offset:52224
	ds_read_b128 v[232:235], v151 offset:53248
	ds_read_b128 v[236:239], v151 offset:54272
	ds_read_b128 v[240:243], v151 offset:55296
	ds_read_b128 v[244:247], v151 offset:56320
	global_load_lds_dwordx4 v[180:181], off
	s_add_i32 m0, s0, 0x2000
	s_add_u32 s86, s86, 0x40080
	v_lshl_add_u64 v[180:181], v[192:193], 0, s[58:59]
	s_addc_u32 s87, s87, 0
	s_add_i32 s0, s96, s1
	global_load_lds_dwordx4 v[180:181], off
	v_lshl_add_u64 v[180:181], s[86:87], 0, v[98:99]
	s_mov_b32 m0, s0
	s_nop 0
	global_load_lds_dwordx4 v[180:181], off
	v_lshl_add_u64 v[180:181], s[86:87], 0, v[134:135]
	s_add_i32 m0, s0, 0x2000
	s_nop 0
	global_load_lds_dwordx4 v[180:181], off
	v_lshl_add_u64 v[180:181], v[248:249], 0, s[58:59]
	s_mov_b32 m0, s42
	s_nop 0
	global_load_lds_dwordx4 v[180:181], off
	v_lshl_add_u64 v[180:181], v[250:251], 0, s[58:59]
	s_mov_b32 m0, s43
	s_nop 0
	global_load_lds_dwordx4 v[180:181], off
	s_waitcnt vmcnt(8)
	s_waitcnt lgkmcnt(0)
	s_barrier
	s_setprio 1
	s_waitcnt lgkmcnt(0)
	v_mfma_f32_16x16x32_bf16 v[60:63], v[140:143], v[188:191], v[60:63]
	v_mfma_f32_16x16x32_bf16 v[56:59], v[156:159], v[188:191], v[56:59]
	v_mfma_f32_16x16x32_bf16 v[44:47], v[140:143], v[224:227], v[44:47]
	v_mfma_f32_16x16x32_bf16 v[40:43], v[156:159], v[224:227], v[40:43]
	v_mfma_f32_16x16x32_bf16 v[28:31], v[140:143], v[232:235], v[28:31]
	v_mfma_f32_16x16x32_bf16 v[24:27], v[156:159], v[232:235], v[24:27]
	v_mfma_f32_16x16x32_bf16 v[12:15], v[140:143], v[240:243], v[12:15]
	v_mfma_f32_16x16x32_bf16 v[8:11], v[156:159], v[240:243], v[8:11]
	v_mfma_f32_16x16x32_bf16 v[60:63], v[152:155], v[220:223], v[60:63]
	v_mfma_f32_16x16x32_bf16 v[56:59], v[160:163], v[220:223], v[56:59]
	v_mfma_f32_16x16x32_bf16 v[44:47], v[152:155], v[228:231], v[44:47]
	v_mfma_f32_16x16x32_bf16 v[40:43], v[160:163], v[228:231], v[40:43]
	v_mfma_f32_16x16x32_bf16 v[28:31], v[152:155], v[236:239], v[28:31]
	v_mfma_f32_16x16x32_bf16 v[24:27], v[160:163], v[236:239], v[24:27]
	v_mfma_f32_16x16x32_bf16 v[12:15], v[152:155], v[244:247], v[12:15]
	v_mfma_f32_16x16x32_bf16 v[8:11], v[160:163], v[244:247], v[8:11]
	s_setprio 0
	s_setprio 1
	v_mfma_f32_16x16x32_bf16 v[52:55], v[164:167], v[188:191], v[52:55]
	v_mfma_f32_16x16x32_bf16 v[48:51], v[172:175], v[188:191], v[48:51]
	v_mfma_f32_16x16x32_bf16 v[36:39], v[164:167], v[224:227], v[36:39]
	v_mfma_f32_16x16x32_bf16 v[32:35], v[172:175], v[224:227], v[32:35]
	v_mfma_f32_16x16x32_bf16 v[20:23], v[164:167], v[232:235], v[20:23]
	v_mfma_f32_16x16x32_bf16 v[16:19], v[172:175], v[232:235], v[16:19]
	v_mfma_f32_16x16x32_bf16 v[4:7], v[164:167], v[240:243], v[4:7]
	v_mfma_f32_16x16x32_bf16 v[0:3], v[172:175], v[240:243], v[0:3]
	v_mfma_f32_16x16x32_bf16 v[52:55], v[168:171], v[220:223], v[52:55]
	v_mfma_f32_16x16x32_bf16 v[48:51], v[176:179], v[220:223], v[48:51]
	v_mfma_f32_16x16x32_bf16 v[36:39], v[168:171], v[228:231], v[36:39]
	v_mfma_f32_16x16x32_bf16 v[32:35], v[176:179], v[228:231], v[32:35]
	v_mfma_f32_16x16x32_bf16 v[20:23], v[168:171], v[236:239], v[20:23]
	v_mfma_f32_16x16x32_bf16 v[16:19], v[176:179], v[236:239], v[16:19]
	v_mfma_f32_16x16x32_bf16 v[4:7], v[168:171], v[244:247], v[4:7]
	v_mfma_f32_16x16x32_bf16 v[0:3], v[176:179], v[244:247], v[0:3]
	s_setprio 0
	s_barrier
	s_add_i32 s90, s90, 2
	s_add_u32 s84, s84, 0x100
	s_addc_u32 s85, s85, 0
	s_add_u32 s75, s75, 0x100
	s_addc_u32 s77, s77, 0
	s_cmp_gt_u32 s90, 13
	s_cbranch_scc1 .Lpeel_exit_232

.Lpeel_exit_232:
	s_and_b64 vcc, exec, s[72:73]
	s_cbranch_vccz .LBB0_235
	s_barrier

.LBB0_309:
	s_add_u32 s84, s84, 0x80
	s_addc_u32 s85, s85, 0
	s_add_u32 s26, s86, 0x100
	s_addc_u32 s27, s87, 0
	s_mov_b32 s0, 0
	s_waitcnt lgkmcnt(0)
	s_waitcnt vmcnt(0)
	s_add_i32 s42, s0, 2
	s_add_u32 s66, s84, 0x80
	s_addc_u32 s86, s85, 0
	s_add_i32 s97, 0, 0x10000
	s_cmp_eq_u32 s88, s0
	s_cselect_b32 s87, s81, s86
	s_cselect_b32 s86, s80, s66
	s_cselect_b32 vcc_hi, s83, s27
	s_cselect_b32 vcc_lo, s82, s26
	s_add_i32 s0, 0, 0x14000
	v_add_u32_e32 v152, s97, v161
	v_add_u32_e32 v172, s0, v161
	ds_read_b128 v[132:135], v152
	ds_read_b128 v[136:139], v152 offset:1024
	ds_read_b128 v[148:151], v152 offset:2048
	ds_read_b128 v[152:155], v152 offset:3072
	ds_read_b128 v[156:159], v172
	ds_read_b128 v[164:167], v172 offset:1024
	ds_read_b128 v[168:171], v172 offset:2048
	ds_read_b128 v[172:175], v172 offset:3072
	v_lshl_add_u64 v[180:181], s[84:85], 0, v[144:145]
	s_add_i32 m0, s23, 0xc000
	ds_read_b128 v[176:179], v163
	ds_read_b128 v[188:191], v163 offset:1024
	ds_read_b128 v[220:223], v163 offset:2048
	ds_read_b128 v[224:227], v163 offset:3072
	ds_read_b128 v[228:231], v163 offset:4096
	ds_read_b128 v[232:235], v163 offset:5120
	ds_read_b128 v[236:239], v163 offset:6144
	ds_read_b128 v[240:243], v163 offset:7168
	global_load_lds_dwordx4 v[180:181], off
	v_lshl_add_u64 v[180:181], s[84:85], 0, v[146:147]
	s_add_i32 m0, s23, 0xe000
	s_nop 0
	global_load_lds_dwordx4 v[180:181], off
	s_waitcnt vmcnt(8)
	s_waitcnt lgkmcnt(0)
	s_barrier
	s_setprio 1
	s_waitcnt lgkmcnt(0)
	v_mfma_f32_16x16x32_bf16 v[128:131], v[132:135], v[176:179], 0
	v_mfma_f32_16x16x32_bf16 v[124:127], v[148:151], v[176:179], 0
	v_mfma_f32_16x16x32_bf16 v[112:115], v[132:135], v[220:223], 0
	v_mfma_f32_16x16x32_bf16 v[108:111], v[148:151], v[220:223], 0
	v_mfma_f32_16x16x32_bf16 v[92:95], v[132:135], v[228:231], 0
	v_mfma_f32_16x16x32_bf16 v[88:91], v[148:151], v[228:231], 0
	v_mfma_f32_16x16x32_bf16 v[76:79], v[132:135], v[236:239], 0
	v_mfma_f32_16x16x32_bf16 v[72:75], v[148:151], v[236:239], 0
	v_mfma_f32_16x16x32_bf16 v[128:131], v[136:139], v[188:191], v[128:131]
	v_mfma_f32_16x16x32_bf16 v[124:127], v[152:155], v[188:191], v[124:127]
	v_mfma_f32_16x16x32_bf16 v[112:115], v[136:139], v[224:227], v[112:115]
	v_mfma_f32_16x16x32_bf16 v[108:111], v[152:155], v[224:227], v[108:111]
	v_mfma_f32_16x16x32_bf16 v[92:95], v[136:139], v[232:235], v[92:95]
	v_mfma_f32_16x16x32_bf16 v[88:91], v[152:155], v[232:235], v[88:91]
	v_mfma_f32_16x16x32_bf16 v[76:79], v[136:139], v[240:243], v[76:79]
	v_mfma_f32_16x16x32_bf16 v[72:75], v[152:155], v[240:243], v[72:75]
	s_setprio 0
	s_setprio 1
	v_mfma_f32_16x16x32_bf16 v[120:123], v[156:159], v[176:179], 0
	v_mfma_f32_16x16x32_bf16 v[116:119], v[168:171], v[176:179], 0
	v_mfma_f32_16x16x32_bf16 v[104:107], v[156:159], v[220:223], 0
	v_mfma_f32_16x16x32_bf16 v[100:103], v[168:171], v[220:223], 0
	v_mfma_f32_16x16x32_bf16 v[84:87], v[156:159], v[228:231], 0
	v_mfma_f32_16x16x32_bf16 v[80:83], v[168:171], v[228:231], 0
	v_mfma_f32_16x16x32_bf16 v[68:71], v[156:159], v[236:239], 0
	v_mfma_f32_16x16x32_bf16 v[64:67], v[168:171], v[236:239], 0
	v_mfma_f32_16x16x32_bf16 v[120:123], v[164:167], v[188:191], v[120:123]
	v_mfma_f32_16x16x32_bf16 v[116:119], v[172:175], v[188:191], v[116:119]
	v_mfma_f32_16x16x32_bf16 v[104:107], v[164:167], v[224:227], v[104:107]
	v_mfma_f32_16x16x32_bf16 v[100:103], v[172:175], v[224:227], v[100:103]
	v_mfma_f32_16x16x32_bf16 v[84:87], v[164:167], v[232:235], v[84:87]
	v_mfma_f32_16x16x32_bf16 v[80:83], v[172:175], v[232:235], v[80:83]
	v_mfma_f32_16x16x32_bf16 v[68:71], v[164:167], v[240:243], v[68:71]
	v_mfma_f32_16x16x32_bf16 v[64:67], v[172:175], v[240:243], v[64:67]
	s_setprio 0
	s_barrier
	s_add_i32 s66, s97, s10
	v_lshl_add_u64 v[180:181], vcc, 0, v[98:99]
	s_mov_b32 m0, s66
	ds_read_b128 v[176:179], v163 offset:16384
	ds_read_b128 v[188:191], v163 offset:17408
	ds_read_b128 v[220:223], v163 offset:18432
	ds_read_b128 v[224:227], v163 offset:19456
	ds_read_b128 v[228:231], v163 offset:20480
	ds_read_b128 v[232:235], v163 offset:21504
	ds_read_b128 v[236:239], v163 offset:22528
	ds_read_b128 v[240:243], v163 offset:23552
	global_load_lds_dwordx4 v[180:181], off
	s_add_i32 m0, s66, 0x2000
	v_lshl_add_u64 v[192:193], vcc, 0, v[142:143]
	s_add_u32 vcc_lo, vcc_lo, s72
	s_addc_u32 vcc_hi, vcc_hi, 0
	s_add_i32 s0, s0, s10
	global_load_lds_dwordx4 v[192:193], off
	v_lshl_add_u64 v[244:245], vcc, 0, v[98:99]
	s_mov_b32 m0, s0
	v_lshl_add_u64 v[246:247], vcc, 0, v[142:143]
	global_load_lds_dwordx4 v[244:245], off
	s_add_i32 m0, s0, 0x2000
	v_lshl_add_u64 v[248:249], s[86:87], 0, v[96:97]
	global_load_lds_dwordx4 v[246:247], off
	s_mov_b32 m0, s23
	v_lshl_add_u64 v[250:251], s[86:87], 0, v[140:141]
	global_load_lds_dwordx4 v[248:249], off
	s_mov_b32 m0, s33
	s_nop 0
	global_load_lds_dwordx4 v[250:251], off
	s_waitcnt vmcnt(8)
	s_waitcnt lgkmcnt(0)
	s_barrier
	s_setprio 1
	s_waitcnt lgkmcnt(0)
	v_mfma_f32_16x16x32_bf16 v[60:63], v[132:135], v[176:179], 0
	v_mfma_f32_16x16x32_bf16 v[56:59], v[148:151], v[176:179], 0
	v_mfma_f32_16x16x32_bf16 v[44:47], v[132:135], v[220:223], 0
	v_mfma_f32_16x16x32_bf16 v[40:43], v[148:151], v[220:223], 0
	v_mfma_f32_16x16x32_bf16 v[28:31], v[132:135], v[228:231], 0
	v_mfma_f32_16x16x32_bf16 v[24:27], v[148:151], v[228:231], 0
	v_mfma_f32_16x16x32_bf16 v[12:15], v[132:135], v[236:239], 0
	v_mfma_f32_16x16x32_bf16 v[8:11], v[148:151], v[236:239], 0
	v_mfma_f32_16x16x32_bf16 v[60:63], v[136:139], v[188:191], v[60:63]
	v_mfma_f32_16x16x32_bf16 v[56:59], v[152:155], v[188:191], v[56:59]
	v_mfma_f32_16x16x32_bf16 v[44:47], v[136:139], v[224:227], v[44:47]
	v_mfma_f32_16x16x32_bf16 v[40:43], v[152:155], v[224:227], v[40:43]
	v_mfma_f32_16x16x32_bf16 v[28:31], v[136:139], v[232:235], v[28:31]
	v_mfma_f32_16x16x32_bf16 v[24:27], v[152:155], v[232:235], v[24:27]
	v_mfma_f32_16x16x32_bf16 v[12:15], v[136:139], v[240:243], v[12:15]
	v_mfma_f32_16x16x32_bf16 v[8:11], v[152:155], v[240:243], v[8:11]
	s_setprio 0
	s_setprio 1
	v_mfma_f32_16x16x32_bf16 v[52:55], v[156:159], v[176:179], 0
	v_mfma_f32_16x16x32_bf16 v[48:51], v[168:171], v[176:179], 0
	v_mfma_f32_16x16x32_bf16 v[36:39], v[156:159], v[220:223], 0
	v_mfma_f32_16x16x32_bf16 v[32:35], v[168:171], v[220:223], 0
	v_mfma_f32_16x16x32_bf16 v[20:23], v[156:159], v[228:231], 0
	v_mfma_f32_16x16x32_bf16 v[16:19], v[168:171], v[228:231], 0
	v_mfma_f32_16x16x32_bf16 v[4:7], v[156:159], v[236:239], 0
	v_mfma_f32_16x16x32_bf16 v[0:3], v[168:171], v[236:239], 0
	v_mfma_f32_16x16x32_bf16 v[52:55], v[164:167], v[188:191], v[52:55]
	v_mfma_f32_16x16x32_bf16 v[48:51], v[172:175], v[188:191], v[48:51]
	v_mfma_f32_16x16x32_bf16 v[36:39], v[164:167], v[224:227], v[36:39]
	v_mfma_f32_16x16x32_bf16 v[32:35], v[172:175], v[224:227], v[32:35]
	v_mfma_f32_16x16x32_bf16 v[20:23], v[164:167], v[232:235], v[20:23]
	v_mfma_f32_16x16x32_bf16 v[16:19], v[172:175], v[232:235], v[16:19]
	v_mfma_f32_16x16x32_bf16 v[4:7], v[164:167], v[240:243], v[4:7]
	v_mfma_f32_16x16x32_bf16 v[0:3], v[172:175], v[240:243], v[0:3]
	s_setprio 0
	s_barrier
	s_add_i32 s0, 0, 0x18000
	s_add_i32 s66, 0, 0x1c000
	v_add_u32_e32 v152, s0, v161
	v_add_u32_e32 v172, s66, v161
	ds_read_b128 v[132:135], v152
	ds_read_b128 v[136:139], v152 offset:1024
	ds_read_b128 v[148:151], v152 offset:2048
	ds_read_b128 v[152:155], v152 offset:3072
	ds_read_b128 v[156:159], v172
	ds_read_b128 v[164:167], v172 offset:1024
	ds_read_b128 v[168:171], v172 offset:2048
	ds_read_b128 v[172:175], v172 offset:3072
	s_add_u32 s86, s86, s72
	s_addc_u32 s87, s87, 0
	s_mov_b32 m0, s43
	v_lshl_add_u64 v[252:253], s[86:87], 0, v[96:97]
	ds_read_b128 v[176:179], v163 offset:32768
	ds_read_b128 v[188:191], v163 offset:33792
	ds_read_b128 v[220:223], v163 offset:34816
	ds_read_b128 v[224:227], v163 offset:35840
	ds_read_b128 v[228:231], v163 offset:36864
	ds_read_b128 v[232:235], v163 offset:37888
	ds_read_b128 v[236:239], v163 offset:38912
	ds_read_b128 v[240:243], v163 offset:39936
	global_load_lds_dwordx4 v[252:253], off
	v_lshl_add_u64 v[252:253], s[86:87], 0, v[140:141]
	s_mov_b32 m0, s44
	s_nop 0
	global_load_lds_dwordx4 v[252:253], off
	s_waitcnt vmcnt(8)
	s_waitcnt lgkmcnt(0)
	s_barrier
	s_setprio 1
	s_waitcnt lgkmcnt(0)
	v_mfma_f32_16x16x32_bf16 v[128:131], v[132:135], v[176:179], v[128:131]
	v_mfma_f32_16x16x32_bf16 v[124:127], v[148:151], v[176:179], v[124:127]
	v_mfma_f32_16x16x32_bf16 v[112:115], v[132:135], v[220:223], v[112:115]
	v_mfma_f32_16x16x32_bf16 v[108:111], v[148:151], v[220:223], v[108:111]
	v_mfma_f32_16x16x32_bf16 v[92:95], v[132:135], v[228:231], v[92:95]
	v_mfma_f32_16x16x32_bf16 v[88:91], v[148:151], v[228:231], v[88:91]
	v_mfma_f32_16x16x32_bf16 v[76:79], v[132:135], v[236:239], v[76:79]
	v_mfma_f32_16x16x32_bf16 v[72:75], v[148:151], v[236:239], v[72:75]
	v_mfma_f32_16x16x32_bf16 v[128:131], v[136:139], v[188:191], v[128:131]
	v_mfma_f32_16x16x32_bf16 v[124:127], v[152:155], v[188:191], v[124:127]
	v_mfma_f32_16x16x32_bf16 v[112:115], v[136:139], v[224:227], v[112:115]
	v_mfma_f32_16x16x32_bf16 v[108:111], v[152:155], v[224:227], v[108:111]
	v_mfma_f32_16x16x32_bf16 v[92:95], v[136:139], v[232:235], v[92:95]
	v_mfma_f32_16x16x32_bf16 v[88:91], v[152:155], v[232:235], v[88:91]
	v_mfma_f32_16x16x32_bf16 v[76:79], v[136:139], v[240:243], v[76:79]
	v_mfma_f32_16x16x32_bf16 v[72:75], v[152:155], v[240:243], v[72:75]
	s_setprio 0
	s_setprio 1
	v_mfma_f32_16x16x32_bf16 v[120:123], v[156:159], v[176:179], v[120:123]
	v_mfma_f32_16x16x32_bf16 v[116:119], v[168:171], v[176:179], v[116:119]
	v_mfma_f32_16x16x32_bf16 v[104:107], v[156:159], v[220:223], v[104:107]
	v_mfma_f32_16x16x32_bf16 v[100:103], v[168:171], v[220:223], v[100:103]
	v_mfma_f32_16x16x32_bf16 v[84:87], v[156:159], v[228:231], v[84:87]
	v_mfma_f32_16x16x32_bf16 v[80:83], v[168:171], v[228:231], v[80:83]
	v_mfma_f32_16x16x32_bf16 v[68:71], v[156:159], v[236:239], v[68:71]
	v_mfma_f32_16x16x32_bf16 v[64:67], v[168:171], v[236:239], v[64:67]
	v_mfma_f32_16x16x32_bf16 v[120:123], v[164:167], v[188:191], v[120:123]
	v_mfma_f32_16x16x32_bf16 v[116:119], v[172:175], v[188:191], v[116:119]
	v_mfma_f32_16x16x32_bf16 v[104:107], v[164:167], v[224:227], v[104:107]
	v_mfma_f32_16x16x32_bf16 v[100:103], v[172:175], v[224:227], v[100:103]
	v_mfma_f32_16x16x32_bf16 v[84:87], v[164:167], v[232:235], v[84:87]
	v_mfma_f32_16x16x32_bf16 v[80:83], v[172:175], v[232:235], v[80:83]
	v_mfma_f32_16x16x32_bf16 v[68:71], v[164:167], v[240:243], v[68:71]
	v_mfma_f32_16x16x32_bf16 v[64:67], v[172:175], v[240:243], v[64:67]
	s_setprio 0
	s_barrier
	s_add_i32 s0, s0, s10
	v_lshl_add_u64 v[180:181], v[180:181], 0, s[58:59]
	s_mov_b32 m0, s0
	ds_read_b128 v[176:179], v163 offset:49152
	ds_read_b128 v[188:191], v163 offset:50176
	ds_read_b128 v[220:223], v163 offset:51200
	ds_read_b128 v[224:227], v163 offset:52224
	ds_read_b128 v[228:231], v163 offset:53248
	ds_read_b128 v[232:235], v163 offset:54272
	ds_read_b128 v[236:239], v163 offset:55296
	ds_read_b128 v[240:243], v163 offset:56320
	global_load_lds_dwordx4 v[180:181], off
	v_lshl_add_u64 v[180:181], v[192:193], 0, s[58:59]
	s_add_i32 m0, s0, 0x2000
	s_add_i32 s0, s66, s10
	global_load_lds_dwordx4 v[180:181], off
	v_lshl_add_u64 v[180:181], v[244:245], 0, s[58:59]
	s_mov_b32 m0, s0
	s_nop 0
	global_load_lds_dwordx4 v[180:181], off
	v_lshl_add_u64 v[180:181], v[246:247], 0, s[58:59]
	s_add_i32 m0, s0, 0x2000
	s_nop 0
	global_load_lds_dwordx4 v[180:181], off
	v_lshl_add_u64 v[180:181], v[248:249], 0, s[58:59]
	s_mov_b32 m0, s47
	s_nop 0
	global_load_lds_dwordx4 v[180:181], off
	v_lshl_add_u64 v[180:181], v[250:251], 0, s[58:59]
	s_mov_b32 m0, s56
	s_nop 0
	global_load_lds_dwordx4 v[180:181], off
	s_waitcnt vmcnt(8)
	s_waitcnt lgkmcnt(0)
	s_barrier
	s_setprio 1
	s_waitcnt lgkmcnt(0)
	v_mfma_f32_16x16x32_bf16 v[60:63], v[132:135], v[176:179], v[60:63]
	v_mfma_f32_16x16x32_bf16 v[56:59], v[148:151], v[176:179], v[56:59]
	v_mfma_f32_16x16x32_bf16 v[44:47], v[132:135], v[220:223], v[44:47]
	v_mfma_f32_16x16x32_bf16 v[40:43], v[148:151], v[220:223], v[40:43]
	v_mfma_f32_16x16x32_bf16 v[28:31], v[132:135], v[228:231], v[28:31]
	v_mfma_f32_16x16x32_bf16 v[24:27], v[148:151], v[228:231], v[24:27]
	v_mfma_f32_16x16x32_bf16 v[12:15], v[132:135], v[236:239], v[12:15]
	v_mfma_f32_16x16x32_bf16 v[8:11], v[148:151], v[236:239], v[8:11]
	v_mfma_f32_16x16x32_bf16 v[60:63], v[136:139], v[188:191], v[60:63]
	v_mfma_f32_16x16x32_bf16 v[56:59], v[152:155], v[188:191], v[56:59]
	v_mfma_f32_16x16x32_bf16 v[44:47], v[136:139], v[224:227], v[44:47]
	v_mfma_f32_16x16x32_bf16 v[40:43], v[152:155], v[224:227], v[40:43]
	v_mfma_f32_16x16x32_bf16 v[28:31], v[136:139], v[232:235], v[28:31]
	v_mfma_f32_16x16x32_bf16 v[24:27], v[152:155], v[232:235], v[24:27]
	v_mfma_f32_16x16x32_bf16 v[12:15], v[136:139], v[240:243], v[12:15]
	v_mfma_f32_16x16x32_bf16 v[8:11], v[152:155], v[240:243], v[8:11]
	s_setprio 0
	s_setprio 1
	v_mfma_f32_16x16x32_bf16 v[52:55], v[156:159], v[176:179], v[52:55]
	v_mfma_f32_16x16x32_bf16 v[48:51], v[168:171], v[176:179], v[48:51]
	v_mfma_f32_16x16x32_bf16 v[36:39], v[156:159], v[220:223], v[36:39]
	v_mfma_f32_16x16x32_bf16 v[32:35], v[168:171], v[220:223], v[32:35]
	v_mfma_f32_16x16x32_bf16 v[20:23], v[156:159], v[228:231], v[20:23]
	v_mfma_f32_16x16x32_bf16 v[16:19], v[168:171], v[228:231], v[16:19]
	v_mfma_f32_16x16x32_bf16 v[4:7], v[156:159], v[236:239], v[4:7]
	v_mfma_f32_16x16x32_bf16 v[0:3], v[168:171], v[236:239], v[0:3]
	v_mfma_f32_16x16x32_bf16 v[52:55], v[164:167], v[188:191], v[52:55]
	v_mfma_f32_16x16x32_bf16 v[48:51], v[172:175], v[188:191], v[48:51]
	v_mfma_f32_16x16x32_bf16 v[36:39], v[164:167], v[224:227], v[36:39]
	v_mfma_f32_16x16x32_bf16 v[32:35], v[172:175], v[224:227], v[32:35]
	v_mfma_f32_16x16x32_bf16 v[20:23], v[164:167], v[232:235], v[20:23]
	v_mfma_f32_16x16x32_bf16 v[16:19], v[172:175], v[232:235], v[16:19]
	v_mfma_f32_16x16x32_bf16 v[4:7], v[164:167], v[240:243], v[4:7]
	v_mfma_f32_16x16x32_bf16 v[0:3], v[172:175], v[240:243], v[0:3]
	s_setprio 0
	s_barrier
	s_add_u32 s84, s84, 0x100
	s_addc_u32 s85, s85, 0
	s_add_u32 s26, s26, 0x100
	s_addc_u32 s27, s27, 0
	s_cmp_ge_u32 s42, s67
	s_mov_b32 s0, s42
	s_cbranch_scc1 .Lpeel_exit_310

.Lpeel_exit_310:
	s_and_b64 vcc, exec, s[78:79]
	s_cbranch_vccz .LBB0_313
	s_barrier

.LBB0_345:
	s_ashr_i32 s71, s70, 31
	s_lshl_b64 s[56:57], s[70:71], 19
	s_add_u32 s74, s12, s56
	s_addc_u32 s75, s13, s57
	s_and_b64 s[56:57], s[72:73], exec
	s_cselect_b32 s27, s75, s79
	s_cselect_b32 s42, s74, s78
	s_ashr_i32 s69, s68, 31
	s_lshl_b64 s[56:57], s[68:69], 19
	s_add_u32 s76, s4, s56
	s_addc_u32 s77, s5, s57
	s_and_b64 s[56:57], s[72:73], exec
	s_cselect_b32 s56, s77, s81
	s_cselect_b32 s57, s76, s80
	s_add_u32 s78, s78, 0x40080
	s_addc_u32 s79, s79, 0
	s_add_u32 s69, s80, 0x100
	s_addc_u32 s71, s81, 0
	s_mov_b32 s84, -2
	s_waitcnt vmcnt(0)
	s_add_u32 s80, s78, 0xfffc0080
	s_addc_u32 s81, s79, -1
	s_add_i32 s85, 0, 0x10000
	s_cmp_eq_u32 s84, 12
	s_cselect_b32 s83, s27, s81
	s_cselect_b32 s82, s42, s80
	s_cselect_b32 s81, s56, s71
	s_cselect_b32 s80, s57, s69
	s_add_i32 s88, 0, 0x14000
	v_add_u32_e32 v160, s85, v145
	v_add_u32_e32 v176, s88, v145
	ds_read_b128 v[140:143], v160
	ds_read_b128 v[152:155], v160 offset:1024
	ds_read_b128 v[156:159], v160 offset:2048
	ds_read_b128 v[160:163], v160 offset:3072
	ds_read_b128 v[164:167], v176
	ds_read_b128 v[168:171], v176 offset:1024
	ds_read_b128 v[172:175], v176 offset:2048
	ds_read_b128 v[176:179], v176 offset:3072
	v_lshl_add_u64 v[180:181], s[78:79], 0, v[136:137]
	s_add_i32 m0, s11, 0xc000
	ds_read_b128 v[188:191], v151
	ds_read_b128 v[220:223], v151 offset:1024
	ds_read_b128 v[224:227], v151 offset:2048
	ds_read_b128 v[228:231], v151 offset:3072
	ds_read_b128 v[232:235], v151 offset:4096
	ds_read_b128 v[236:239], v151 offset:5120
	ds_read_b128 v[240:243], v151 offset:6144
	ds_read_b128 v[244:247], v151 offset:7168
	global_load_lds_dwordx4 v[180:181], off
	v_lshl_add_u64 v[180:181], s[78:79], 0, v[138:139]
	s_add_i32 m0, s11, 0xe000
	s_nop 0
	global_load_lds_dwordx4 v[180:181], off
	s_waitcnt vmcnt(8)
	s_waitcnt lgkmcnt(0)
	s_barrier
	s_setprio 1
	s_waitcnt lgkmcnt(0)
	v_mfma_f32_16x16x32_bf16 v[128:131], v[140:143], v[188:191], 0
	v_mfma_f32_16x16x32_bf16 v[120:123], v[156:159], v[188:191], 0
	v_mfma_f32_16x16x32_bf16 v[112:115], v[140:143], v[224:227], 0
	v_mfma_f32_16x16x32_bf16 v[104:107], v[156:159], v[224:227], 0
	v_mfma_f32_16x16x32_bf16 v[92:95], v[140:143], v[232:235], 0
	v_mfma_f32_16x16x32_bf16 v[84:87], v[156:159], v[232:235], 0
	v_mfma_f32_16x16x32_bf16 v[76:79], v[140:143], v[240:243], 0
	v_mfma_f32_16x16x32_bf16 v[68:71], v[156:159], v[240:243], 0
	v_mfma_f32_16x16x32_bf16 v[128:131], v[152:155], v[220:223], v[128:131]
	v_mfma_f32_16x16x32_bf16 v[120:123], v[160:163], v[220:223], v[120:123]
	v_mfma_f32_16x16x32_bf16 v[112:115], v[152:155], v[228:231], v[112:115]
	v_mfma_f32_16x16x32_bf16 v[104:107], v[160:163], v[228:231], v[104:107]
	v_mfma_f32_16x16x32_bf16 v[92:95], v[152:155], v[236:239], v[92:95]
	v_mfma_f32_16x16x32_bf16 v[84:87], v[160:163], v[236:239], v[84:87]
	v_mfma_f32_16x16x32_bf16 v[76:79], v[152:155], v[244:247], v[76:79]
	v_mfma_f32_16x16x32_bf16 v[68:71], v[160:163], v[244:247], v[68:71]
	s_setprio 0
	s_setprio 1
	v_mfma_f32_16x16x32_bf16 v[124:127], v[164:167], v[188:191], 0
	v_mfma_f32_16x16x32_bf16 v[116:119], v[172:175], v[188:191], 0
	v_mfma_f32_16x16x32_bf16 v[108:111], v[164:167], v[224:227], 0
	v_mfma_f32_16x16x32_bf16 v[100:103], v[172:175], v[224:227], 0
	v_mfma_f32_16x16x32_bf16 v[88:91], v[164:167], v[232:235], 0
	v_mfma_f32_16x16x32_bf16 v[80:83], v[172:175], v[232:235], 0
	v_mfma_f32_16x16x32_bf16 v[72:75], v[164:167], v[240:243], 0
	v_mfma_f32_16x16x32_bf16 v[64:67], v[172:175], v[240:243], 0
	v_mfma_f32_16x16x32_bf16 v[124:127], v[168:171], v[220:223], v[124:127]
	v_mfma_f32_16x16x32_bf16 v[116:119], v[176:179], v[220:223], v[116:119]
	v_mfma_f32_16x16x32_bf16 v[108:111], v[168:171], v[228:231], v[108:111]
	v_mfma_f32_16x16x32_bf16 v[100:103], v[176:179], v[228:231], v[100:103]
	v_mfma_f32_16x16x32_bf16 v[88:91], v[168:171], v[236:239], v[88:91]
	v_mfma_f32_16x16x32_bf16 v[80:83], v[176:179], v[236:239], v[80:83]
	v_mfma_f32_16x16x32_bf16 v[72:75], v[168:171], v[244:247], v[72:75]
	v_mfma_f32_16x16x32_bf16 v[64:67], v[176:179], v[244:247], v[64:67]
	s_setprio 0
	s_barrier
	s_add_i32 s85, s85, s10
	v_lshl_add_u64 v[180:181], s[80:81], 0, v[98:99]
	s_mov_b32 m0, s85
	ds_read_b128 v[188:191], v151 offset:16384
	ds_read_b128 v[220:223], v151 offset:17408
	ds_read_b128 v[224:227], v151 offset:18432
	ds_read_b128 v[228:231], v151 offset:19456
	ds_read_b128 v[232:235], v151 offset:20480
	ds_read_b128 v[236:239], v151 offset:21504
	ds_read_b128 v[240:243], v151 offset:22528
	ds_read_b128 v[244:247], v151 offset:23552
	global_load_lds_dwordx4 v[180:181], off
	s_add_i32 m0, s85, 0x2000
	s_add_u32 s86, s80, 0x40000
	v_lshl_add_u64 v[192:193], s[80:81], 0, v[134:135]
	s_addc_u32 s87, s81, 0
	s_add_i32 s85, s88, s10
	global_load_lds_dwordx4 v[192:193], off
	v_lshl_add_u64 v[248:249], s[86:87], 0, v[98:99]
	s_mov_b32 m0, s85
	v_lshl_add_u64 v[250:251], s[82:83], 0, v[132:133]
	global_load_lds_dwordx4 v[248:249], off
	v_lshl_add_u64 v[248:249], s[86:87], 0, v[134:135]
	s_add_i32 m0, s85, 0x2000
	s_nop 0
	global_load_lds_dwordx4 v[248:249], off
	v_lshl_add_u64 v[248:249], s[82:83], 0, v[96:97]
	s_mov_b32 m0, s11
	s_nop 0
	global_load_lds_dwordx4 v[248:249], off
	s_mov_b32 m0, s20
	s_nop 0
	global_load_lds_dwordx4 v[250:251], off
	s_waitcnt vmcnt(8)
	s_waitcnt lgkmcnt(0)
	s_barrier
	s_setprio 1
	s_waitcnt lgkmcnt(0)
	v_mfma_f32_16x16x32_bf16 v[60:63], v[140:143], v[188:191], 0
	v_mfma_f32_16x16x32_bf16 v[52:55], v[156:159], v[188:191], 0
	v_mfma_f32_16x16x32_bf16 v[44:47], v[140:143], v[224:227], 0
	v_mfma_f32_16x16x32_bf16 v[36:39], v[156:159], v[224:227], 0
	v_mfma_f32_16x16x32_bf16 v[28:31], v[140:143], v[232:235], 0
	v_mfma_f32_16x16x32_bf16 v[20:23], v[156:159], v[232:235], 0
	v_mfma_f32_16x16x32_bf16 v[12:15], v[140:143], v[240:243], 0
	v_mfma_f32_16x16x32_bf16 v[4:7], v[156:159], v[240:243], 0
	v_mfma_f32_16x16x32_bf16 v[60:63], v[152:155], v[220:223], v[60:63]
	v_mfma_f32_16x16x32_bf16 v[52:55], v[160:163], v[220:223], v[52:55]
	v_mfma_f32_16x16x32_bf16 v[44:47], v[152:155], v[228:231], v[44:47]
	v_mfma_f32_16x16x32_bf16 v[36:39], v[160:163], v[228:231], v[36:39]
	v_mfma_f32_16x16x32_bf16 v[28:31], v[152:155], v[236:239], v[28:31]
	v_mfma_f32_16x16x32_bf16 v[20:23], v[160:163], v[236:239], v[20:23]
	v_mfma_f32_16x16x32_bf16 v[12:15], v[152:155], v[244:247], v[12:15]
	v_mfma_f32_16x16x32_bf16 v[4:7], v[160:163], v[244:247], v[4:7]
	s_setprio 0
	s_setprio 1
	v_mfma_f32_16x16x32_bf16 v[56:59], v[164:167], v[188:191], 0
	v_mfma_f32_16x16x32_bf16 v[48:51], v[172:175], v[188:191], 0
	v_mfma_f32_16x16x32_bf16 v[40:43], v[164:167], v[224:227], 0
	v_mfma_f32_16x16x32_bf16 v[32:35], v[172:175], v[224:227], 0
	v_mfma_f32_16x16x32_bf16 v[24:27], v[164:167], v[232:235], 0
	v_mfma_f32_16x16x32_bf16 v[16:19], v[172:175], v[232:235], 0
	v_mfma_f32_16x16x32_bf16 v[8:11], v[164:167], v[240:243], 0
	v_mfma_f32_16x16x32_bf16 v[0:3], v[172:175], v[240:243], 0
	v_mfma_f32_16x16x32_bf16 v[56:59], v[168:171], v[220:223], v[56:59]
	v_mfma_f32_16x16x32_bf16 v[48:51], v[176:179], v[220:223], v[48:51]
	v_mfma_f32_16x16x32_bf16 v[40:43], v[168:171], v[228:231], v[40:43]
	v_mfma_f32_16x16x32_bf16 v[32:35], v[176:179], v[228:231], v[32:35]
	v_mfma_f32_16x16x32_bf16 v[24:27], v[168:171], v[236:239], v[24:27]
	v_mfma_f32_16x16x32_bf16 v[16:19], v[176:179], v[236:239], v[16:19]
	v_mfma_f32_16x16x32_bf16 v[8:11], v[168:171], v[244:247], v[8:11]
	v_mfma_f32_16x16x32_bf16 v[0:3], v[176:179], v[244:247], v[0:3]
	s_setprio 0
	s_barrier
	s_add_i32 s85, 0, 0x18000
	s_add_i32 s86, 0, 0x1c000
	v_add_u32_e32 v160, s85, v145
	v_add_u32_e32 v176, s86, v145
	ds_read_b128 v[140:143], v160
	ds_read_b128 v[152:155], v160 offset:1024
	ds_read_b128 v[156:159], v160 offset:2048
	ds_read_b128 v[160:163], v160 offset:3072
	ds_read_b128 v[164:167], v176
	ds_read_b128 v[168:171], v176 offset:1024
	ds_read_b128 v[172:175], v176 offset:2048
	ds_read_b128 v[176:179], v176 offset:3072
	s_add_u32 s82, s82, 0x40000
	s_addc_u32 s83, s83, 0
	s_mov_b32 m0, s22
	v_lshl_add_u64 v[252:253], s[82:83], 0, v[96:97]
	ds_read_b128 v[188:191], v151 offset:32768
	ds_read_b128 v[220:223], v151 offset:33792
	ds_read_b128 v[224:227], v151 offset:34816
	ds_read_b128 v[228:231], v151 offset:35840
	ds_read_b128 v[232:235], v151 offset:36864
	ds_read_b128 v[236:239], v151 offset:37888
	ds_read_b128 v[240:243], v151 offset:38912
	ds_read_b128 v[244:247], v151 offset:39936
	global_load_lds_dwordx4 v[252:253], off
	v_lshl_add_u64 v[252:253], s[82:83], 0, v[132:133]
	s_mov_b32 m0, s23
	s_nop 0
	global_load_lds_dwordx4 v[252:253], off
	s_waitcnt vmcnt(8)
	s_waitcnt lgkmcnt(0)
	s_barrier
	s_setprio 1
	s_waitcnt lgkmcnt(0)
	v_mfma_f32_16x16x32_bf16 v[128:131], v[140:143], v[188:191], v[128:131]
	v_mfma_f32_16x16x32_bf16 v[120:123], v[156:159], v[188:191], v[120:123]
	v_mfma_f32_16x16x32_bf16 v[112:115], v[140:143], v[224:227], v[112:115]
	v_mfma_f32_16x16x32_bf16 v[104:107], v[156:159], v[224:227], v[104:107]
	v_mfma_f32_16x16x32_bf16 v[92:95], v[140:143], v[232:235], v[92:95]
	v_mfma_f32_16x16x32_bf16 v[84:87], v[156:159], v[232:235], v[84:87]
	v_mfma_f32_16x16x32_bf16 v[76:79], v[140:143], v[240:243], v[76:79]
	v_mfma_f32_16x16x32_bf16 v[68:71], v[156:159], v[240:243], v[68:71]
	v_mfma_f32_16x16x32_bf16 v[128:131], v[152:155], v[220:223], v[128:131]
	v_mfma_f32_16x16x32_bf16 v[120:123], v[160:163], v[220:223], v[120:123]
	v_mfma_f32_16x16x32_bf16 v[112:115], v[152:155], v[228:231], v[112:115]
	v_mfma_f32_16x16x32_bf16 v[104:107], v[160:163], v[228:231], v[104:107]
	v_mfma_f32_16x16x32_bf16 v[92:95], v[152:155], v[236:239], v[92:95]
	v_mfma_f32_16x16x32_bf16 v[84:87], v[160:163], v[236:239], v[84:87]
	v_mfma_f32_16x16x32_bf16 v[76:79], v[152:155], v[244:247], v[76:79]
	v_mfma_f32_16x16x32_bf16 v[68:71], v[160:163], v[244:247], v[68:71]
	s_setprio 0
	s_setprio 1
	v_mfma_f32_16x16x32_bf16 v[124:127], v[164:167], v[188:191], v[124:127]
	v_mfma_f32_16x16x32_bf16 v[116:119], v[172:175], v[188:191], v[116:119]
	v_mfma_f32_16x16x32_bf16 v[108:111], v[164:167], v[224:227], v[108:111]
	v_mfma_f32_16x16x32_bf16 v[100:103], v[172:175], v[224:227], v[100:103]
	v_mfma_f32_16x16x32_bf16 v[88:91], v[164:167], v[232:235], v[88:91]
	v_mfma_f32_16x16x32_bf16 v[80:83], v[172:175], v[232:235], v[80:83]
	v_mfma_f32_16x16x32_bf16 v[72:75], v[164:167], v[240:243], v[72:75]
	v_mfma_f32_16x16x32_bf16 v[64:67], v[172:175], v[240:243], v[64:67]
	v_mfma_f32_16x16x32_bf16 v[124:127], v[168:171], v[220:223], v[124:127]
	v_mfma_f32_16x16x32_bf16 v[116:119], v[176:179], v[220:223], v[116:119]
	v_mfma_f32_16x16x32_bf16 v[108:111], v[168:171], v[228:231], v[108:111]
	v_mfma_f32_16x16x32_bf16 v[100:103], v[176:179], v[228:231], v[100:103]
	v_mfma_f32_16x16x32_bf16 v[88:91], v[168:171], v[236:239], v[88:91]
	v_mfma_f32_16x16x32_bf16 v[80:83], v[176:179], v[236:239], v[80:83]
	v_mfma_f32_16x16x32_bf16 v[72:75], v[168:171], v[244:247], v[72:75]
	v_mfma_f32_16x16x32_bf16 v[64:67], v[176:179], v[244:247], v[64:67]
	s_setprio 0
	s_barrier
	s_add_i32 s82, s85, s10
	v_lshl_add_u64 v[180:181], v[180:181], 0, s[58:59]
	s_mov_b32 m0, s82
	ds_read_b128 v[188:191], v151 offset:49152
	ds_read_b128 v[220:223], v151 offset:50176
	ds_read_b128 v[224:227], v151 offset:51200
	ds_read_b128 v[228:231], v151 offset:52224
	ds_read_b128 v[232:235], v151 offset:53248
	ds_read_b128 v[236:239], v151 offset:54272
	ds_read_b128 v[240:243], v151 offset:55296
	ds_read_b128 v[244:247], v151 offset:56320
	global_load_lds_dwordx4 v[180:181], off
	s_add_i32 m0, s82, 0x2000
	s_add_u32 s80, s80, 0x40080
	v_lshl_add_u64 v[180:181], v[192:193], 0, s[58:59]
	s_addc_u32 s81, s81, 0
	s_add_i32 s82, s86, s10
	global_load_lds_dwordx4 v[180:181], off
	v_lshl_add_u64 v[180:181], s[80:81], 0, v[98:99]
	s_mov_b32 m0, s82
	s_nop 0
	global_load_lds_dwordx4 v[180:181], off
	v_lshl_add_u64 v[180:181], s[80:81], 0, v[134:135]
	s_add_i32 m0, s82, 0x2000
	s_nop 0
	global_load_lds_dwordx4 v[180:181], off
	v_lshl_add_u64 v[180:181], v[248:249], 0, s[58:59]
	s_mov_b32 m0, s33
	s_nop 0
	global_load_lds_dwordx4 v[180:181], off
	v_lshl_add_u64 v[180:181], v[250:251], 0, s[58:59]
	s_mov_b32 m0, s43
	s_nop 0
	global_load_lds_dwordx4 v[180:181], off
	s_waitcnt vmcnt(8)
	s_waitcnt lgkmcnt(0)
	s_barrier
	s_setprio 1
	s_waitcnt lgkmcnt(0)
	v_mfma_f32_16x16x32_bf16 v[60:63], v[140:143], v[188:191], v[60:63]
	v_mfma_f32_16x16x32_bf16 v[52:55], v[156:159], v[188:191], v[52:55]
	v_mfma_f32_16x16x32_bf16 v[44:47], v[140:143], v[224:227], v[44:47]
	v_mfma_f32_16x16x32_bf16 v[36:39], v[156:159], v[224:227], v[36:39]
	v_mfma_f32_16x16x32_bf16 v[28:31], v[140:143], v[232:235], v[28:31]
	v_mfma_f32_16x16x32_bf16 v[20:23], v[156:159], v[232:235], v[20:23]
	v_mfma_f32_16x16x32_bf16 v[12:15], v[140:143], v[240:243], v[12:15]
	v_mfma_f32_16x16x32_bf16 v[4:7], v[156:159], v[240:243], v[4:7]
	v_mfma_f32_16x16x32_bf16 v[60:63], v[152:155], v[220:223], v[60:63]
	v_mfma_f32_16x16x32_bf16 v[52:55], v[160:163], v[220:223], v[52:55]
	v_mfma_f32_16x16x32_bf16 v[44:47], v[152:155], v[228:231], v[44:47]
	v_mfma_f32_16x16x32_bf16 v[36:39], v[160:163], v[228:231], v[36:39]
	v_mfma_f32_16x16x32_bf16 v[28:31], v[152:155], v[236:239], v[28:31]
	v_mfma_f32_16x16x32_bf16 v[20:23], v[160:163], v[236:239], v[20:23]
	v_mfma_f32_16x16x32_bf16 v[12:15], v[152:155], v[244:247], v[12:15]
	v_mfma_f32_16x16x32_bf16 v[4:7], v[160:163], v[244:247], v[4:7]
	s_setprio 0
	s_setprio 1
	v_mfma_f32_16x16x32_bf16 v[56:59], v[164:167], v[188:191], v[56:59]
	v_mfma_f32_16x16x32_bf16 v[48:51], v[172:175], v[188:191], v[48:51]
	v_mfma_f32_16x16x32_bf16 v[40:43], v[164:167], v[224:227], v[40:43]
	v_mfma_f32_16x16x32_bf16 v[32:35], v[172:175], v[224:227], v[32:35]
	v_mfma_f32_16x16x32_bf16 v[24:27], v[164:167], v[232:235], v[24:27]
	v_mfma_f32_16x16x32_bf16 v[16:19], v[172:175], v[232:235], v[16:19]
	v_mfma_f32_16x16x32_bf16 v[8:11], v[164:167], v[240:243], v[8:11]
	v_mfma_f32_16x16x32_bf16 v[0:3], v[172:175], v[240:243], v[0:3]
	v_mfma_f32_16x16x32_bf16 v[56:59], v[168:171], v[220:223], v[56:59]
	v_mfma_f32_16x16x32_bf16 v[48:51], v[176:179], v[220:223], v[48:51]
	v_mfma_f32_16x16x32_bf16 v[40:43], v[168:171], v[228:231], v[40:43]
	v_mfma_f32_16x16x32_bf16 v[32:35], v[176:179], v[228:231], v[32:35]
	v_mfma_f32_16x16x32_bf16 v[24:27], v[168:171], v[236:239], v[24:27]
	v_mfma_f32_16x16x32_bf16 v[16:19], v[176:179], v[236:239], v[16:19]
	v_mfma_f32_16x16x32_bf16 v[8:11], v[168:171], v[244:247], v[8:11]
	v_mfma_f32_16x16x32_bf16 v[0:3], v[176:179], v[244:247], v[0:3]
	s_setprio 0
	s_barrier
	s_add_i32 s84, s84, 2
	s_add_u32 s78, s78, 0x100
	s_addc_u32 s79, s79, 0
	s_add_u32 s69, s69, 0x100
	s_addc_u32 s71, s71, 0
	s_cmp_gt_u32 s84, 13
	s_cbranch_scc1 .Lpeel_exit_346

.Lpeel_exit_346:
	s_and_b64 vcc, exec, s[66:67]
	s_cbranch_vccz .LBB0_349
	s_barrier
